# M3 q.n dot: 8-lane reduction via DPP instead of three ds_bpermute round trips
# baseline (speedup 1.0000x reference)
.LBB0_731:
	s_or_b64 exec, exec, s[0:1]
	v_and_b32_e32 v96, 7, v157
	v_mul_lo_u32 v2, v160, s48
	v_lshlrev_b32_e32 v3, 5, v96
	v_add3_u32 v2, 0, v2, v3
	ds_read_b128 v[68:71], v2
	v_lshl_add_u32 v3, v96, 6, 0
	v_add_u32_e32 v3, 0x18500, v3
	ds_read_b128 v[72:75], v2 offset:16
	ds_read_b128 v[76:79], v3
	ds_read_b128 v[80:83], v3 offset:16
	ds_read_b128 v[84:87], v3 offset:32
	ds_read_b128 v[92:95], v3 offset:48
	s_waitcnt lgkmcnt(5)
	v_lshlrev_b32_e32 v2, 16, v68
	v_and_b32_e32 v3, 0xffff0000, v68
	v_and_b32_e32 v68, 64, v150
	s_waitcnt lgkmcnt(3)
	v_fma_f32 v2, v76, v2, 0
	v_fmac_f32_e32 v2, v77, v3
	v_lshlrev_b32_e32 v3, 16, v69
	v_fmac_f32_e32 v2, v78, v3
	v_and_b32_e32 v3, 0xffff0000, v69
	v_fmac_f32_e32 v2, v79, v3
	v_lshlrev_b32_e32 v3, 16, v70
	s_waitcnt lgkmcnt(2)
	v_fmac_f32_e32 v2, v80, v3
	v_and_b32_e32 v3, 0xffff0000, v70
	v_fmac_f32_e32 v2, v81, v3
	v_lshlrev_b32_e32 v3, 16, v71
	v_fmac_f32_e32 v2, v82, v3
	v_and_b32_e32 v3, 0xffff0000, v71
	v_fmac_f32_e32 v2, v83, v3
	v_lshlrev_b32_e32 v3, 16, v72
	s_waitcnt lgkmcnt(1)
	v_fmac_f32_e32 v2, v84, v3
	v_and_b32_e32 v3, 0xffff0000, v72
	v_fmac_f32_e32 v2, v85, v3
	v_lshlrev_b32_e32 v3, 16, v73
	v_fmac_f32_e32 v2, v86, v3
	v_and_b32_e32 v3, 0xffff0000, v73
	v_fmac_f32_e32 v2, v87, v3
	v_lshlrev_b32_e32 v3, 16, v74
	s_waitcnt lgkmcnt(0)
	v_fmac_f32_e32 v2, v92, v3
	v_and_b32_e32 v3, 0xffff0000, v74
	v_fmac_f32_e32 v2, v93, v3
	v_lshlrev_b32_e32 v3, 16, v75
	v_fmac_f32_e32 v2, v94, v3
	v_and_b32_e32 v3, 0xffff0000, v75
	v_fmac_f32_e32 v2, v95, v3
	s_nop 1
	v_add_f32_dpp v2, v2, v2 quad_perm:[1,0,3,2] row_mask:0xf bank_mask:0xf
	s_nop 1
	v_add_f32_dpp v2, v2, v2 quad_perm:[2,3,0,1] row_mask:0xf bank_mask:0xf
	s_nop 1
	v_mov_b32_dpp v3, v2 row_half_mirror row_mask:0xf bank_mask:0xf
	v_cmp_eq_u32_e64 s[0:1], 0, v96
	s_and_saveexec_b64 s[2:3], s[0:1]
	s_cbranch_execz .LBB0_733
	v_lshl_add_u32 v68, v160, 2, 0
	v_add_u32_e32 v68, 0x18000, v68
	s_waitcnt lgkmcnt(0)
	v_add_f32_e32 v2, v2, v3
	ds_write_b32 v68, v2
